# prompt-side compression finisher: the rolled 8-iteration accumulator read-back loop (one device-scope load round trip per iteration) unrolled so its 24 loads are issued together; on top of version 42
# speedup vs baseline: 1.0096x; 1.0032x over previous
.LBB0_1322:
	v_ashrrev_i32_e32 v30, 11, v17
	v_lshl_or_b32 v26, v30, 7, v15
	v_ashrrev_i32_e32 v27, 31, v26
	v_lshlrev_b64 v[26:27], 2, v[26:27]
	global_load_dword v242, v[24:25], off sc1
	v_lshl_add_u64 v[28:29], s[20:21], 0, v[26:27]
	v_lshl_add_u64 v[26:27], s[52:53], 0, v[26:27]
	global_load_dword v250, v[28:29], off
	s_nop 0
	global_load_dword v202, v[26:27], off
	v_lshl_add_u64 v[24:25], v[24:25], 0, s[12:13]
	v_add_u32_e32 v17, 0x200, v17
	v_ashrrev_i32_e32 v30, 11, v17
	v_lshl_or_b32 v26, v30, 7, v15
	v_ashrrev_i32_e32 v27, 31, v26
	v_lshlrev_b64 v[26:27], 2, v[26:27]
	global_load_dword v243, v[24:25], off sc1
	v_lshl_add_u64 v[28:29], s[20:21], 0, v[26:27]
	v_lshl_add_u64 v[26:27], s[52:53], 0, v[26:27]
	global_load_dword v251, v[28:29], off
	s_nop 0
	global_load_dword v203, v[26:27], off
	v_lshl_add_u64 v[24:25], v[24:25], 0, s[12:13]
	v_add_u32_e32 v17, 0x200, v17
	v_ashrrev_i32_e32 v30, 11, v17
	v_lshl_or_b32 v26, v30, 7, v15
	v_ashrrev_i32_e32 v27, 31, v26
	v_lshlrev_b64 v[26:27], 2, v[26:27]
	global_load_dword v244, v[24:25], off sc1
	v_lshl_add_u64 v[28:29], s[20:21], 0, v[26:27]
	v_lshl_add_u64 v[26:27], s[52:53], 0, v[26:27]
	global_load_dword v252, v[28:29], off
	s_nop 0
	global_load_dword v204, v[26:27], off
	v_lshl_add_u64 v[24:25], v[24:25], 0, s[12:13]
	v_add_u32_e32 v17, 0x200, v17
	v_ashrrev_i32_e32 v30, 11, v17
	v_lshl_or_b32 v26, v30, 7, v15
	v_ashrrev_i32_e32 v27, 31, v26
	v_lshlrev_b64 v[26:27], 2, v[26:27]
	global_load_dword v245, v[24:25], off sc1
	v_lshl_add_u64 v[28:29], s[20:21], 0, v[26:27]
	v_lshl_add_u64 v[26:27], s[52:53], 0, v[26:27]
	global_load_dword v253, v[28:29], off
	s_nop 0
	global_load_dword v205, v[26:27], off
	v_lshl_add_u64 v[24:25], v[24:25], 0, s[12:13]
	v_add_u32_e32 v17, 0x200, v17
	v_ashrrev_i32_e32 v30, 11, v17
	v_lshl_or_b32 v26, v30, 7, v15
	v_ashrrev_i32_e32 v27, 31, v26
	v_lshlrev_b64 v[26:27], 2, v[26:27]
	global_load_dword v246, v[24:25], off sc1
	v_lshl_add_u64 v[28:29], s[20:21], 0, v[26:27]
	v_lshl_add_u64 v[26:27], s[52:53], 0, v[26:27]
	global_load_dword v254, v[28:29], off
	s_nop 0
	global_load_dword v206, v[26:27], off
	v_lshl_add_u64 v[24:25], v[24:25], 0, s[12:13]
	v_add_u32_e32 v17, 0x200, v17
	v_ashrrev_i32_e32 v30, 11, v17
	v_lshl_or_b32 v26, v30, 7, v15
	v_ashrrev_i32_e32 v27, 31, v26
	v_lshlrev_b64 v[26:27], 2, v[26:27]
	global_load_dword v247, v[24:25], off sc1
	v_lshl_add_u64 v[28:29], s[20:21], 0, v[26:27]
	v_lshl_add_u64 v[26:27], s[52:53], 0, v[26:27]
	global_load_dword v255, v[28:29], off
	s_nop 0
	global_load_dword v207, v[26:27], off
	v_lshl_add_u64 v[24:25], v[24:25], 0, s[12:13]
	v_add_u32_e32 v17, 0x200, v17
	v_ashrrev_i32_e32 v30, 11, v17
	v_lshl_or_b32 v26, v30, 7, v15
	v_ashrrev_i32_e32 v27, 31, v26
	v_lshlrev_b64 v[26:27], 2, v[26:27]
	global_load_dword v248, v[24:25], off sc1
	v_lshl_add_u64 v[28:29], s[20:21], 0, v[26:27]
	v_lshl_add_u64 v[26:27], s[52:53], 0, v[26:27]
	global_load_dword v200, v[28:29], off
	s_nop 0
	global_load_dword v208, v[26:27], off
	v_lshl_add_u64 v[24:25], v[24:25], 0, s[12:13]
	v_add_u32_e32 v17, 0x200, v17
	v_ashrrev_i32_e32 v30, 11, v17
	v_lshl_or_b32 v26, v30, 7, v15
	v_ashrrev_i32_e32 v27, 31, v26
	v_lshlrev_b64 v[26:27], 2, v[26:27]
	global_load_dword v249, v[24:25], off sc1
	v_lshl_add_u64 v[28:29], s[20:21], 0, v[26:27]
	v_lshl_add_u64 v[26:27], s[52:53], 0, v[26:27]
	global_load_dword v201, v[28:29], off
	s_nop 0
	global_load_dword v209, v[26:27], off
	v_lshl_add_u64 v[24:25], v[24:25], 0, s[12:13]
	v_add_u32_e32 v17, 0x200, v17
	v_mov_b32_e32 v17, v2
	s_waitcnt vmcnt(21)
	v_add_f32_e32 v28, v250, v242
	v_add_f32_e32 v28, v28, v202
	v_mul_f32_e32 v26, 0xbfb8aa3b, v28
	v_exp_f32_e32 v26, v26
	v_ashrrev_i32_e32 v30, 11, v17
	v_add_f32_e32 v29, 1.0, v26
	v_rcp_f32_e32 v29, v29
	v_bfe_u32 v27, v17, 7, 4
	v_lshl_or_b32 v27, v30, 4, v27
	v_mad_u64_u32 v[26:27], s[22:23], v27, s44, v[16:17]
	v_mul_f32_e32 v27, v28, v29
	v_cvt_pk_bf16_f32 v27, v27, s0
	ds_write_b16 v26, v27 offset:33792
	v_add_u32_e32 v17, 0x200, v17
	s_waitcnt vmcnt(18)
	v_add_f32_e32 v28, v251, v243
	v_add_f32_e32 v28, v28, v203
	v_mul_f32_e32 v26, 0xbfb8aa3b, v28
	v_exp_f32_e32 v26, v26
	v_ashrrev_i32_e32 v30, 11, v17
	v_add_f32_e32 v29, 1.0, v26
	v_rcp_f32_e32 v29, v29
	v_bfe_u32 v27, v17, 7, 4
	v_lshl_or_b32 v27, v30, 4, v27
	v_mad_u64_u32 v[26:27], s[22:23], v27, s44, v[16:17]
	v_mul_f32_e32 v27, v28, v29
	v_cvt_pk_bf16_f32 v27, v27, s0
	ds_write_b16 v26, v27 offset:33792
	v_add_u32_e32 v17, 0x200, v17
	s_waitcnt vmcnt(15)
	v_add_f32_e32 v28, v252, v244
	v_add_f32_e32 v28, v28, v204
	v_mul_f32_e32 v26, 0xbfb8aa3b, v28
	v_exp_f32_e32 v26, v26
	v_ashrrev_i32_e32 v30, 11, v17
	v_add_f32_e32 v29, 1.0, v26
	v_rcp_f32_e32 v29, v29
	v_bfe_u32 v27, v17, 7, 4
	v_lshl_or_b32 v27, v30, 4, v27
	v_mad_u64_u32 v[26:27], s[22:23], v27, s44, v[16:17]
	v_mul_f32_e32 v27, v28, v29
	v_cvt_pk_bf16_f32 v27, v27, s0
	ds_write_b16 v26, v27 offset:33792
	v_add_u32_e32 v17, 0x200, v17
	s_waitcnt vmcnt(12)
	v_add_f32_e32 v28, v253, v245
	v_add_f32_e32 v28, v28, v205
	v_mul_f32_e32 v26, 0xbfb8aa3b, v28
	v_exp_f32_e32 v26, v26
	v_ashrrev_i32_e32 v30, 11, v17
	v_add_f32_e32 v29, 1.0, v26
	v_rcp_f32_e32 v29, v29
	v_bfe_u32 v27, v17, 7, 4
	v_lshl_or_b32 v27, v30, 4, v27
	v_mad_u64_u32 v[26:27], s[22:23], v27, s44, v[16:17]
	v_mul_f32_e32 v27, v28, v29
	v_cvt_pk_bf16_f32 v27, v27, s0
	ds_write_b16 v26, v27 offset:33792
	v_add_u32_e32 v17, 0x200, v17
	s_waitcnt vmcnt(9)
	v_add_f32_e32 v28, v254, v246
	v_add_f32_e32 v28, v28, v206
	v_mul_f32_e32 v26, 0xbfb8aa3b, v28
	v_exp_f32_e32 v26, v26
	v_ashrrev_i32_e32 v30, 11, v17
	v_add_f32_e32 v29, 1.0, v26
	v_rcp_f32_e32 v29, v29
	v_bfe_u32 v27, v17, 7, 4
	v_lshl_or_b32 v27, v30, 4, v27
	v_mad_u64_u32 v[26:27], s[22:23], v27, s44, v[16:17]
	v_mul_f32_e32 v27, v28, v29
	v_cvt_pk_bf16_f32 v27, v27, s0
	ds_write_b16 v26, v27 offset:33792
	v_add_u32_e32 v17, 0x200, v17
	s_waitcnt vmcnt(6)
	v_add_f32_e32 v28, v255, v247
	v_add_f32_e32 v28, v28, v207
	v_mul_f32_e32 v26, 0xbfb8aa3b, v28
	v_exp_f32_e32 v26, v26
	v_ashrrev_i32_e32 v30, 11, v17
	v_add_f32_e32 v29, 1.0, v26
	v_rcp_f32_e32 v29, v29
	v_bfe_u32 v27, v17, 7, 4
	v_lshl_or_b32 v27, v30, 4, v27
	v_mad_u64_u32 v[26:27], s[22:23], v27, s44, v[16:17]
	v_mul_f32_e32 v27, v28, v29
	v_cvt_pk_bf16_f32 v27, v27, s0
	ds_write_b16 v26, v27 offset:33792
	v_add_u32_e32 v17, 0x200, v17
	s_waitcnt vmcnt(3)
	v_add_f32_e32 v28, v200, v248
	v_add_f32_e32 v28, v28, v208
	v_mul_f32_e32 v26, 0xbfb8aa3b, v28
	v_exp_f32_e32 v26, v26
	v_ashrrev_i32_e32 v30, 11, v17
	v_add_f32_e32 v29, 1.0, v26
	v_rcp_f32_e32 v29, v29
	v_bfe_u32 v27, v17, 7, 4
	v_lshl_or_b32 v27, v30, 4, v27
	v_mad_u64_u32 v[26:27], s[22:23], v27, s44, v[16:17]
	v_mul_f32_e32 v27, v28, v29
	v_cvt_pk_bf16_f32 v27, v27, s0
	ds_write_b16 v26, v27 offset:33792
	v_add_u32_e32 v17, 0x200, v17
	s_waitcnt vmcnt(0)
	v_add_f32_e32 v28, v201, v249
	v_add_f32_e32 v28, v28, v209
	v_mul_f32_e32 v26, 0xbfb8aa3b, v28
	v_exp_f32_e32 v26, v26
	v_ashrrev_i32_e32 v30, 11, v17
	v_add_f32_e32 v29, 1.0, v26
	v_rcp_f32_e32 v29, v29
	v_bfe_u32 v27, v17, 7, 4
	v_lshl_or_b32 v27, v30, 4, v27
	v_mad_u64_u32 v[26:27], s[22:23], v27, s44, v[16:17]
	v_mul_f32_e32 v27, v28, v29
	v_cvt_pk_bf16_f32 v27, v27, s0
	ds_write_b16 v26, v27 offset:33792
	v_add_u32_e32 v17, 0x200, v17
	s_branch .LBB0_1311
